# same single-raise priority pattern extended to the Q-up, K-up, V-up and gate GEMM loops
# speedup vs baseline: 1.0181x; 1.0032x over previous
; DEV float bf2f(u16 h) { return __uint_as_float(((unsigned)h) << 16); }
;     ...
;       __syncthreads();
; #pragma unroll
;       for (int i = 0; i < 4; ++i) {
;         *(bf16x8*)(sA + (srow + 32 * i) * LDT + scol) = ra[d][i];
;         *(bf16x8*)(sB + (srow + 32 * i) * LDT + scol) = rb[d][i];
;         if (SS) {
;           bf16x8 v = (SS == 1) ? ra[d][i] : rb[d][i];
; #pragma unroll
;           for (int j = 0; j < 8; ++j) {
;             float f = bf2f((u16)v[j]);
;             ssq[i] += f * f;
;           }
;         }
;       }
;       __syncthreads();
;       if (kt + d + DEPTH < nk) {
; #pragma unroll
;         for (int i = 0; i < 4; ++i) {
;           ra[d][i] = *(const bf16x8*)(ap + (size_t)(32 * i) * lda);
;           rb[d][i] = *(const bf16x8*)(bp + (size_t)(32 * i) * ldb);
;         }
;         ap += 64;
;         bp += 64;
;       }
; #pragma unroll
;       for (int ks = 0; ks < 4; ++ks) {
;         bf16x8 af[2], bfr[2];
; #pragma unroll
;         for (int i = 0; i < 2; ++i) {
;           af[i] = *(const bf16x8*)(sA + (wm * 64 + i * 32) * LDT + fro + ks * 16);
;           bfr[i] = *(const bf16x8*)(sB + (wn * 64 + i * 32) * LDT + fro + ks * 16);
;         }
;         __builtin_amdgcn_s_setprio(1);
; #pragma unroll
;         for (int mi = 0; mi < 2; ++mi)
; #pragma unroll
;           for (int ni = 0; ni < 2; ++ni)
;             acc[mi][ni] = __builtin_amdgcn_mfma_f32_32x32x16_bf16(af[mi], bfr[ni], acc[mi][ni], 0, 0, 0);
;         __builtin_amdgcn_s_setprio(0);
;       }
.LBB0_624:
	s_setprio 1
	v_lshlrev_b32_e32 v187, 16, v92
	v_lshlrev_b32_e32 v186, 16, v84
	v_pk_fma_f32 v[120:121], v[186:187], v[186:187], v[120:121]
	v_and_b32_e32 v187, 0xffff0000, v92
	v_and_b32_e32 v186, 0xffff0000, v84
	v_pk_fma_f32 v[120:121], v[186:187], v[186:187], v[120:121]
	v_lshlrev_b32_e32 v187, 16, v93
	v_lshlrev_b32_e32 v186, 16, v85
	v_pk_fma_f32 v[120:121], v[186:187], v[186:187], v[120:121]
	v_and_b32_e32 v93, 0xffff0000, v93
	v_and_b32_e32 v92, 0xffff0000, v85
	v_pk_fma_f32 v[84:85], v[92:93], v[92:93], v[120:121]
	v_lshlrev_b32_e32 v93, 16, v94
	v_lshlrev_b32_e32 v92, 16, v86
	v_pk_fma_f32 v[84:85], v[92:93], v[92:93], v[84:85]
	v_and_b32_e32 v93, 0xffff0000, v94
	v_and_b32_e32 v92, 0xffff0000, v86
	v_pk_fma_f32 v[84:85], v[92:93], v[92:93], v[84:85]
	v_lshlrev_b32_e32 v93, 16, v95
	v_lshlrev_b32_e32 v92, 16, v87
	v_pk_fma_f32 v[84:85], v[92:93], v[92:93], v[84:85]
	v_and_b32_e32 v93, 0xffff0000, v95
	v_and_b32_e32 v92, 0xffff0000, v87
	v_pk_fma_f32 v[120:121], v[92:93], v[92:93], v[84:85]
	v_lshlrev_b32_e32 v85, 16, v88
	v_lshlrev_b32_e32 v84, 16, v80
	v_pk_fma_f32 v[84:85], v[84:85], v[84:85], v[116:117]
	v_and_b32_e32 v87, 0xffff0000, v88
	v_and_b32_e32 v86, 0xffff0000, v80
	v_pk_fma_f32 v[84:85], v[86:87], v[86:87], v[84:85]
	v_lshlrev_b32_e32 v87, 16, v89
	v_lshlrev_b32_e32 v86, 16, v81
	v_pk_fma_f32 v[84:85], v[86:87], v[86:87], v[84:85]
	v_and_b32_e32 v87, 0xffff0000, v89
	v_and_b32_e32 v86, 0xffff0000, v81
	v_pk_fma_f32 v[80:81], v[86:87], v[86:87], v[84:85]
	v_lshlrev_b32_e32 v85, 16, v90
	v_lshlrev_b32_e32 v84, 16, v82
	v_pk_fma_f32 v[80:81], v[84:85], v[84:85], v[80:81]
	v_and_b32_e32 v85, 0xffff0000, v90
	v_and_b32_e32 v84, 0xffff0000, v82
	v_pk_fma_f32 v[80:81], v[84:85], v[84:85], v[80:81]
	v_lshlrev_b32_e32 v85, 16, v91
	v_lshlrev_b32_e32 v84, 16, v83
	v_pk_fma_f32 v[80:81], v[84:85], v[84:85], v[80:81]
	v_and_b32_e32 v85, 0xffff0000, v91
	v_and_b32_e32 v84, 0xffff0000, v83
	v_pk_fma_f32 v[116:117], v[84:85], v[84:85], v[80:81]
	ds_read_b128 v[80:83], v119
	ds_read_b128 v[84:87], v184 offset:18432
	ds_read_b128 v[88:91], v119 offset:4608
	ds_read_b128 v[92:95], v184 offset:23040
	s_waitcnt lgkmcnt(2)
	v_mfma_f32_32x32x16_bf16 v[48:63], v[80:83], v[84:87], v[48:63]
	s_waitcnt lgkmcnt(0)
	v_mfma_f32_32x32x16_bf16 v[32:47], v[80:83], v[92:95], v[32:47]
	v_mfma_f32_32x32x16_bf16 v[16:31], v[88:91], v[84:87], v[16:31]
	v_mfma_f32_32x32x16_bf16 v[0:15], v[88:91], v[92:95], v[0:15]
	ds_read_b128 v[80:83], v119 offset:32
	ds_read_b128 v[84:87], v119 offset:4640
	ds_read_b128 v[88:91], v184 offset:18464
	ds_read_b128 v[92:95], v184 offset:23072
	s_waitcnt lgkmcnt(1)
	v_mfma_f32_32x32x16_bf16 v[48:63], v[80:83], v[88:91], v[48:63]
	s_waitcnt lgkmcnt(0)
	v_mfma_f32_32x32x16_bf16 v[32:47], v[80:83], v[92:95], v[32:47]
	v_mfma_f32_32x32x16_bf16 v[16:31], v[84:87], v[88:91], v[16:31]
	v_mfma_f32_32x32x16_bf16 v[0:15], v[84:87], v[92:95], v[0:15]
	ds_read_b128 v[80:83], v119 offset:64
	ds_read_b128 v[84:87], v119 offset:4672
	ds_read_b128 v[88:91], v184 offset:18496
	ds_read_b128 v[92:95], v184 offset:23104
	s_waitcnt lgkmcnt(1)
	v_mfma_f32_32x32x16_bf16 v[48:63], v[80:83], v[88:91], v[48:63]
	s_waitcnt lgkmcnt(0)
	v_mfma_f32_32x32x16_bf16 v[32:47], v[80:83], v[92:95], v[32:47]
	v_mfma_f32_32x32x16_bf16 v[16:31], v[84:87], v[88:91], v[16:31]
	v_mfma_f32_32x32x16_bf16 v[0:15], v[84:87], v[92:95], v[0:15]
	ds_read_b128 v[80:83], v119 offset:96
	ds_read_b128 v[84:87], v119 offset:4704
	ds_read_b128 v[88:91], v184 offset:18528
	ds_read_b128 v[92:95], v184 offset:23136
	s_waitcnt lgkmcnt(1)
	v_mfma_f32_32x32x16_bf16 v[48:63], v[80:83], v[88:91], v[48:63]
	s_waitcnt lgkmcnt(0)
	v_mfma_f32_32x32x16_bf16 v[32:47], v[80:83], v[92:95], v[32:47]
	v_mfma_f32_32x32x16_bf16 v[16:31], v[84:87], v[88:91], v[16:31]
	v_mfma_f32_32x32x16_bf16 v[0:15], v[84:87], v[92:95], v[0:15]
	s_setprio 0
	s_add_i32 s4, s4, -1
	s_cmp_eq_u32 s4, 0
	s_waitcnt vmcnt(7)
	v_mov_b32_e32 v84, v96
	v_mov_b32_e32 v85, v97
	v_mov_b32_e32 v86, v98
	v_mov_b32_e32 v87, v99
	s_waitcnt vmcnt(5)
	v_mov_b32_e32 v92, v100
	v_mov_b32_e32 v93, v101
	v_mov_b32_e32 v94, v102
	v_mov_b32_e32 v95, v103
	s_waitcnt vmcnt(3)
	v_mov_b32_e32 v80, v104
	v_mov_b32_e32 v81, v105
	v_mov_b32_e32 v82, v106
	v_mov_b32_e32 v83, v107
	s_waitcnt vmcnt(1)
	v_mov_b32_e32 v88, v108
	v_mov_b32_e32 v89, v109
	v_mov_b32_e32 v90, v110
	v_mov_b32_e32 v91, v111
	s_cbranch_scc1 .LBB0_627

; DEV float bf2f(u16 h) { return __uint_as_float(((unsigned)h) << 16); }
;     ...
;       __syncthreads();
; #pragma unroll
;       for (int i = 0; i < 4; ++i) {
;         *(bf16x8*)(sA + (srow + 32 * i) * LDT + scol) = ra[d][i];
;         *(bf16x8*)(sB + (srow + 32 * i) * LDT + scol) = rb[d][i];
;         if (SS) {
;           bf16x8 v = (SS == 1) ? ra[d][i] : rb[d][i];
; #pragma unroll
;           for (int j = 0; j < 8; ++j) {
;             float f = bf2f((u16)v[j]);
;             ssq[i] += f * f;
;           }
;         }
;       }
;       __syncthreads();
;       if (kt + d + DEPTH < nk) {
; #pragma unroll
;         for (int i = 0; i < 4; ++i) {
;           ra[d][i] = *(const bf16x8*)(ap + (size_t)(32 * i) * lda);
;           rb[d][i] = *(const bf16x8*)(bp + (size_t)(32 * i) * ldb);
;         }
;         ap += 64;
;         bp += 64;
;       }
; #pragma unroll
;       for (int ks = 0; ks < 4; ++ks) {
;         bf16x8 af[2], bfr[2];
; #pragma unroll
;         for (int i = 0; i < 2; ++i) {
;           af[i] = *(const bf16x8*)(sA + (wm * 64 + i * 32) * LDT + fro + ks * 16);
;           bfr[i] = *(const bf16x8*)(sB + (wn * 64 + i * 32) * LDT + fro + ks * 16);
;         }
;         __builtin_amdgcn_s_setprio(1);
; #pragma unroll
;         for (int mi = 0; mi < 2; ++mi)
; #pragma unroll
;           for (int ni = 0; ni < 2; ++ni)
;             acc[mi][ni] = __builtin_amdgcn_mfma_f32_32x32x16_bf16(af[mi], bfr[ni], acc[mi][ni], 0, 0, 0);
;         __builtin_amdgcn_s_setprio(0);
;       }
.LBB0_712:
	s_setprio 1
	v_lshlrev_b32_e32 v177, 16, v124
	v_lshlrev_b32_e32 v176, 16, v120
	v_pk_fma_f32 v[170:171], v[176:177], v[176:177], v[170:171]
	v_and_b32_e32 v177, 0xffff0000, v124
	v_and_b32_e32 v176, 0xffff0000, v120
	v_pk_fma_f32 v[170:171], v[176:177], v[176:177], v[170:171]
	v_lshlrev_b32_e32 v177, 16, v125
	v_lshlrev_b32_e32 v176, 16, v121
	v_pk_fma_f32 v[170:171], v[176:177], v[176:177], v[170:171]
	v_and_b32_e32 v125, 0xffff0000, v125
	v_and_b32_e32 v124, 0xffff0000, v121
	v_pk_fma_f32 v[120:121], v[124:125], v[124:125], v[170:171]
	v_lshlrev_b32_e32 v125, 16, v126
	v_lshlrev_b32_e32 v124, 16, v122
	v_pk_fma_f32 v[120:121], v[124:125], v[124:125], v[120:121]
	v_and_b32_e32 v125, 0xffff0000, v126
	v_and_b32_e32 v124, 0xffff0000, v122
	v_pk_fma_f32 v[120:121], v[124:125], v[124:125], v[120:121]
	v_lshlrev_b32_e32 v125, 16, v112
	v_lshlrev_b32_e32 v124, 16, v116
	v_lshlrev_b32_e32 v171, 16, v127
	v_and_b32_e32 v175, 0xffff0000, v127
	v_pk_fma_f32 v[124:125], v[124:125], v[124:125], v[168:169]
	v_and_b32_e32 v127, 0xffff0000, v112
	v_and_b32_e32 v126, 0xffff0000, v116
	v_pk_fma_f32 v[124:125], v[126:127], v[126:127], v[124:125]
	v_lshlrev_b32_e32 v127, 16, v113
	v_lshlrev_b32_e32 v126, 16, v117
	v_lshlrev_b32_e32 v170, 16, v123
	v_pk_fma_f32 v[124:125], v[126:127], v[126:127], v[124:125]
	v_and_b32_e32 v113, 0xffff0000, v113
	v_and_b32_e32 v112, 0xffff0000, v117
	v_and_b32_e32 v174, 0xffff0000, v123
	v_pk_fma_f32 v[120:121], v[170:171], v[170:171], v[120:121]
	v_pk_fma_f32 v[112:113], v[112:113], v[112:113], v[124:125]
	v_lshlrev_b32_e32 v117, 16, v114
	v_lshlrev_b32_e32 v116, 16, v118
	v_pk_fma_f32 v[120:121], v[174:175], v[174:175], v[120:121]
	v_pk_fma_f32 v[112:113], v[116:117], v[116:117], v[112:113]
	v_and_b32_e32 v117, 0xffff0000, v114
	v_and_b32_e32 v116, 0xffff0000, v118
	v_lshlrev_b32_e32 v125, 16, v115
	v_and_b32_e32 v123, 0xffff0000, v115
	v_lshlrev_b32_e32 v115, 16, v108
	v_lshlrev_b32_e32 v114, 16, v104
	v_pk_fma_f32 v[112:113], v[116:117], v[116:117], v[112:113]
	v_pk_fma_f32 v[114:115], v[114:115], v[114:115], v[120:121]
	v_and_b32_e32 v117, 0xffff0000, v108
	v_and_b32_e32 v116, 0xffff0000, v104
	v_pk_fma_f32 v[114:115], v[116:117], v[116:117], v[114:115]
	v_lshlrev_b32_e32 v117, 16, v109
	v_lshlrev_b32_e32 v116, 16, v105
	v_pk_fma_f32 v[114:115], v[116:117], v[116:117], v[114:115]
	v_and_b32_e32 v109, 0xffff0000, v109
	v_and_b32_e32 v108, 0xffff0000, v105
	v_pk_fma_f32 v[104:105], v[108:109], v[108:109], v[114:115]
	v_lshlrev_b32_e32 v109, 16, v110
	v_lshlrev_b32_e32 v108, 16, v106
	v_pk_fma_f32 v[104:105], v[108:109], v[108:109], v[104:105]
	v_and_b32_e32 v109, 0xffff0000, v110
	v_and_b32_e32 v108, 0xffff0000, v106
	v_lshlrev_b32_e32 v124, 16, v119
	v_pk_fma_f32 v[104:105], v[108:109], v[108:109], v[104:105]
	v_lshlrev_b32_e32 v109, 16, v111
	v_lshlrev_b32_e32 v108, 16, v107
	v_and_b32_e32 v122, 0xffff0000, v119
	v_pk_fma_f32 v[112:113], v[124:125], v[124:125], v[112:113]
	v_pk_fma_f32 v[104:105], v[108:109], v[108:109], v[104:105]
	v_and_b32_e32 v109, 0xffff0000, v111
	v_and_b32_e32 v108, 0xffff0000, v107
	v_pk_fma_f32 v[112:113], v[122:123], v[122:123], v[112:113]
	v_pk_fma_f32 v[170:171], v[108:109], v[108:109], v[104:105]
	v_lshlrev_b32_e32 v105, 16, v100
	v_lshlrev_b32_e32 v104, 16, v96
	v_pk_fma_f32 v[104:105], v[104:105], v[104:105], v[112:113]
	v_and_b32_e32 v107, 0xffff0000, v100
	v_and_b32_e32 v106, 0xffff0000, v96
	v_pk_fma_f32 v[104:105], v[106:107], v[106:107], v[104:105]
	v_lshlrev_b32_e32 v107, 16, v101
	v_lshlrev_b32_e32 v106, 16, v97
	v_pk_fma_f32 v[104:105], v[106:107], v[106:107], v[104:105]
	v_and_b32_e32 v101, 0xffff0000, v101
	v_and_b32_e32 v100, 0xffff0000, v97
	v_pk_fma_f32 v[96:97], v[100:101], v[100:101], v[104:105]
	ds_read_b128 v[104:107], v161
	ds_read_b128 v[108:111], v161 offset:4608
	ds_read_b128 v[112:115], v167 offset:18432
	ds_read_b128 v[116:119], v167 offset:23040
	v_lshlrev_b32_e32 v101, 16, v102
	v_lshlrev_b32_e32 v100, 16, v98
	v_pk_fma_f32 v[96:97], v[100:101], v[100:101], v[96:97]
	v_and_b32_e32 v101, 0xffff0000, v102
	v_and_b32_e32 v100, 0xffff0000, v98
	v_pk_fma_f32 v[96:97], v[100:101], v[100:101], v[96:97]
	v_lshlrev_b32_e32 v101, 16, v103
	v_lshlrev_b32_e32 v100, 16, v99
	v_pk_fma_f32 v[96:97], v[100:101], v[100:101], v[96:97]
	v_and_b32_e32 v101, 0xffff0000, v103
	v_and_b32_e32 v100, 0xffff0000, v99
	v_pk_fma_f32 v[168:169], v[100:101], v[100:101], v[96:97]
	s_xor_b64 s[12:13], s[4:5], -1
	s_waitcnt lgkmcnt(1)
	v_mfma_f32_32x32x16_bf16 v[48:63], v[104:107], v[112:115], v[48:63]
	s_waitcnt lgkmcnt(0)
	v_mfma_f32_32x32x16_bf16 v[32:47], v[104:107], v[116:119], v[32:47]
	v_mfma_f32_32x32x16_bf16 v[16:31], v[108:111], v[112:115], v[16:31]
	v_mfma_f32_32x32x16_bf16 v[0:15], v[108:111], v[116:119], v[0:15]
	ds_read_b128 v[96:99], v161 offset:32
	ds_read_b128 v[100:103], v161 offset:4640
	ds_read_b128 v[104:107], v167 offset:18464
	ds_read_b128 v[108:111], v167 offset:23072
	s_waitcnt lgkmcnt(1)
	v_mfma_f32_32x32x16_bf16 v[48:63], v[96:99], v[104:107], v[48:63]
	s_waitcnt lgkmcnt(0)
	v_mfma_f32_32x32x16_bf16 v[32:47], v[96:99], v[108:111], v[32:47]
	v_mfma_f32_32x32x16_bf16 v[16:31], v[100:103], v[104:107], v[16:31]
	v_mfma_f32_32x32x16_bf16 v[0:15], v[100:103], v[108:111], v[0:15]
	ds_read_b128 v[96:99], v161 offset:64
	ds_read_b128 v[100:103], v161 offset:4672
	ds_read_b128 v[104:107], v167 offset:18496
	ds_read_b128 v[108:111], v167 offset:23104
	s_waitcnt lgkmcnt(1)
	v_mfma_f32_32x32x16_bf16 v[48:63], v[96:99], v[104:107], v[48:63]
	s_waitcnt lgkmcnt(0)
	v_mfma_f32_32x32x16_bf16 v[32:47], v[96:99], v[108:111], v[32:47]
	v_mfma_f32_32x32x16_bf16 v[16:31], v[100:103], v[104:107], v[16:31]
	v_mfma_f32_32x32x16_bf16 v[0:15], v[100:103], v[108:111], v[0:15]
	ds_read_b128 v[96:99], v161 offset:96
	ds_read_b128 v[100:103], v161 offset:4704
	ds_read_b128 v[104:107], v167 offset:18528
	ds_read_b128 v[108:111], v167 offset:23136
	s_waitcnt lgkmcnt(1)
	v_mfma_f32_32x32x16_bf16 v[48:63], v[96:99], v[104:107], v[48:63]
	s_waitcnt lgkmcnt(0)
	v_mfma_f32_32x32x16_bf16 v[32:47], v[96:99], v[108:111], v[32:47]
	v_mfma_f32_32x32x16_bf16 v[16:31], v[100:103], v[104:107], v[16:31]
	v_mfma_f32_32x32x16_bf16 v[0:15], v[100:103], v[108:111], v[0:15]
	s_setprio 0
	s_waitcnt vmcnt(2)
	v_mov_b64_e32 v[100:101], v[156:157]
	v_mov_b64_e32 v[96:97], v[152:153]
	v_mov_b64_e32 v[108:109], v[148:149]
	v_mov_b64_e32 v[104:105], v[144:145]
	v_mov_b64_e32 v[112:113], v[140:141]
	v_mov_b64_e32 v[116:117], v[136:137]
	v_mov_b64_e32 v[124:125], v[132:133]
	v_mov_b64_e32 v[120:121], v[128:129]
	s_mov_b64 s[4:5], 0
	s_and_b64 vcc, exec, s[12:13]
	v_mov_b64_e32 v[102:103], v[158:159]
	v_mov_b64_e32 v[98:99], v[154:155]
	v_mov_b64_e32 v[110:111], v[150:151]
	v_mov_b64_e32 v[106:107], v[146:147]
	v_mov_b64_e32 v[114:115], v[142:143]
	v_mov_b64_e32 v[118:119], v[138:139]
	v_mov_b64_e32 v[126:127], v[134:135]
	v_mov_b64_e32 v[122:123], v[130:131]
	s_cbranch_vccnz .LBB0_718

; DEV float bf2f(u16 h) { return __uint_as_float(((unsigned)h) << 16); }
;     ...
;     for (int d = 0; d < DEPTH; ++d) {
;       __syncthreads();
; #pragma unroll
;       for (int i = 0; i < 4; ++i) {
;         *(bf16x8*)(sA + (srow + 32 * i) * LDT + scol) = ra[d][i];
;         *(bf16x8*)(sB + (srow + 32 * i) * LDT + scol) = rb[d][i];
;         if (SS) {
;           bf16x8 v = (SS == 1) ? ra[d][i] : rb[d][i];
; #pragma unroll
;           for (int j = 0; j < 8; ++j) {
;             float f = bf2f((u16)v[j]);
;             ssq[i] += f * f;
;           }
;         }
;       }
;       __syncthreads();
;       if (kt + d + DEPTH < nk) {
; #pragma unroll
;         for (int i = 0; i < 4; ++i) {
;           ra[d][i] = *(const bf16x8*)(ap + (size_t)(32 * i) * lda);
;           rb[d][i] = *(const bf16x8*)(bp + (size_t)(32 * i) * ldb);
;         }
;         ap += 64;
;         bp += 64;
;       }
; #pragma unroll
;       for (int ks = 0; ks < 4; ++ks) {
;         bf16x8 af[2], bfr[2];
; #pragma unroll
;         for (int i = 0; i < 2; ++i) {
;           af[i] = *(const bf16x8*)(sA + (wm * 64 + i * 32) * LDT + fro + ks * 16);
;           bfr[i] = *(const bf16x8*)(sB + (wn * 64 + i * 32) * LDT + fro + ks * 16);
;         }
;         __builtin_amdgcn_s_setprio(1);
; #pragma unroll
;         for (int mi = 0; mi < 2; ++mi)
; #pragma unroll
;           for (int ni = 0; ni < 2; ++ni)
;             acc[mi][ni] = __builtin_amdgcn_mfma_f32_32x32x16_bf16(af[mi], bfr[ni], acc[mi][ni], 0, 0, 0);
;         __builtin_amdgcn_s_setprio(0);
;       }
.LBB0_716:
	s_setprio 1
	ds_read_b128 v[144:147], v161
	ds_read_b128 v[148:151], v161 offset:4608
	ds_read_b128 v[152:155], v167 offset:18432
	ds_read_b128 v[156:159], v167 offset:23040
	s_waitcnt lgkmcnt(1)
	v_mfma_f32_32x32x16_bf16 v[48:63], v[144:147], v[152:155], v[48:63]
	s_waitcnt lgkmcnt(0)
	v_mfma_f32_32x32x16_bf16 v[32:47], v[144:147], v[156:159], v[32:47]
	v_mfma_f32_32x32x16_bf16 v[16:31], v[148:151], v[152:155], v[16:31]
	v_mfma_f32_32x32x16_bf16 v[0:15], v[148:151], v[156:159], v[0:15]
	ds_read_b128 v[144:147], v161 offset:32
	ds_read_b128 v[148:151], v161 offset:4640
	ds_read_b128 v[152:155], v167 offset:18464
	ds_read_b128 v[156:159], v167 offset:23072
	s_waitcnt lgkmcnt(1)
	v_mfma_f32_32x32x16_bf16 v[48:63], v[144:147], v[152:155], v[48:63]
	s_waitcnt lgkmcnt(0)
	v_mfma_f32_32x32x16_bf16 v[32:47], v[144:147], v[156:159], v[32:47]
	v_mfma_f32_32x32x16_bf16 v[16:31], v[148:151], v[152:155], v[16:31]
	v_mfma_f32_32x32x16_bf16 v[0:15], v[148:151], v[156:159], v[0:15]
	ds_read_b128 v[144:147], v161 offset:64
	ds_read_b128 v[148:151], v161 offset:4672
	ds_read_b128 v[152:155], v167 offset:18496
	ds_read_b128 v[156:159], v167 offset:23104
	s_waitcnt lgkmcnt(1)
	v_mfma_f32_32x32x16_bf16 v[48:63], v[144:147], v[152:155], v[48:63]
	s_waitcnt lgkmcnt(0)
	v_mfma_f32_32x32x16_bf16 v[32:47], v[144:147], v[156:159], v[32:47]
	v_mfma_f32_32x32x16_bf16 v[16:31], v[148:151], v[152:155], v[16:31]
	v_mfma_f32_32x32x16_bf16 v[0:15], v[148:151], v[156:159], v[0:15]
	ds_read_b128 v[144:147], v161 offset:96
	ds_read_b128 v[148:151], v161 offset:4704
	ds_read_b128 v[152:155], v167 offset:18528
	ds_read_b128 v[156:159], v167 offset:23136
	s_waitcnt lgkmcnt(1)
	v_mfma_f32_32x32x16_bf16 v[48:63], v[144:147], v[152:155], v[48:63]
	s_waitcnt lgkmcnt(0)
	v_mfma_f32_32x32x16_bf16 v[32:47], v[144:147], v[156:159], v[32:47]
	v_mfma_f32_32x32x16_bf16 v[16:31], v[148:151], v[152:155], v[16:31]
	v_mfma_f32_32x32x16_bf16 v[0:15], v[148:151], v[156:159], v[0:15]
	s_setprio 0
	s_andn2_b64 vcc, exec, s[4:5]
	s_barrier
	ds_write_b128 v166, v[104:107]
	ds_write_b128 v166, v[84:87] offset:18432
	ds_write_b128 v166, v[108:111] offset:4608
	ds_write_b128 v166, v[68:71] offset:23040
	ds_write_b128 v166, v[96:99] offset:9216
	ds_write_b128 v166, v[76:79] offset:27648
	ds_write_b128 v166, v[100:103] offset:13824
	s_waitcnt vmcnt(0)
	ds_write_b128 v166, v[92:95] offset:32256
	s_waitcnt lgkmcnt(0)
	s_barrier
	s_cbranch_vccz .LBB0_711
	v_mov_b64_e32 v[158:159], v[102:103]
	v_mov_b64_e32 v[154:155], v[98:99]
	v_mov_b64_e32 v[150:151], v[110:111]
	v_mov_b64_e32 v[146:147], v[106:107]
	v_mov_b64_e32 v[156:157], v[100:101]
	v_mov_b64_e32 v[152:153], v[96:97]
	v_mov_b64_e32 v[148:149], v[108:109]
	v_mov_b64_e32 v[144:145], v[104:105]
	s_branch .LBB0_712

; DEV float bf2f(u16 h) { return __uint_as_float(((unsigned)h) << 16); }
;     ...
;       __syncthreads();
; #pragma unroll
;       for (int i = 0; i < 4; ++i) {
;         *(bf16x8*)(sA + (srow + 32 * i) * LDT + scol) = ra[d][i];
;         *(bf16x8*)(sB + (srow + 32 * i) * LDT + scol) = rb[d][i];
;         if (SS) {
;           bf16x8 v = (SS == 1) ? ra[d][i] : rb[d][i];
; #pragma unroll
;           for (int j = 0; j < 8; ++j) {
;             float f = bf2f((u16)v[j]);
;             ssq[i] += f * f;
;           }
;         }
;       }
;       __syncthreads();
;       if (kt + d + DEPTH < nk) {
; #pragma unroll
;         for (int i = 0; i < 4; ++i) {
;           ra[d][i] = *(const bf16x8*)(ap + (size_t)(32 * i) * lda);
;           rb[d][i] = *(const bf16x8*)(bp + (size_t)(32 * i) * ldb);
;         }
;         ap += 64;
;         bp += 64;
;       }
; #pragma unroll
;       for (int ks = 0; ks < 4; ++ks) {
;         bf16x8 af[2], bfr[2];
; #pragma unroll
;         for (int i = 0; i < 2; ++i) {
;           af[i] = *(const bf16x8*)(sA + (wm * 64 + i * 32) * LDT + fro + ks * 16);
;           bfr[i] = *(const bf16x8*)(sB + (wn * 64 + i * 32) * LDT + fro + ks * 16);
;         }
;         __builtin_amdgcn_s_setprio(1);
; #pragma unroll
;         for (int mi = 0; mi < 2; ++mi)
; #pragma unroll
;           for (int ni = 0; ni < 2; ++ni)
;             acc[mi][ni] = __builtin_amdgcn_mfma_f32_32x32x16_bf16(af[mi], bfr[ni], acc[mi][ni], 0, 0, 0);
;         __builtin_amdgcn_s_setprio(0);
;       }
.LBB0_731:
	s_setprio 1
	v_lshlrev_b32_e32 v177, 16, v120
	v_lshlrev_b32_e32 v176, 16, v124
	v_pk_fma_f32 v[168:169], v[176:177], v[176:177], v[168:169]
	v_and_b32_e32 v177, 0xffff0000, v120
	v_and_b32_e32 v176, 0xffff0000, v124
	v_pk_fma_f32 v[168:169], v[176:177], v[176:177], v[168:169]
	v_lshlrev_b32_e32 v177, 16, v121
	v_lshlrev_b32_e32 v176, 16, v125
	v_pk_fma_f32 v[168:169], v[176:177], v[176:177], v[168:169]
	v_and_b32_e32 v121, 0xffff0000, v121
	v_and_b32_e32 v120, 0xffff0000, v125
	v_pk_fma_f32 v[120:121], v[120:121], v[120:121], v[168:169]
	v_lshlrev_b32_e32 v125, 16, v122
	v_lshlrev_b32_e32 v124, 16, v126
	v_pk_fma_f32 v[120:121], v[124:125], v[124:125], v[120:121]
	v_and_b32_e32 v125, 0xffff0000, v122
	v_and_b32_e32 v124, 0xffff0000, v126
	v_pk_fma_f32 v[120:121], v[124:125], v[124:125], v[120:121]
	v_lshlrev_b32_e32 v125, 16, v112
	v_lshlrev_b32_e32 v124, 16, v116
	v_and_b32_e32 v174, 0xffff0000, v127
	v_lshlrev_b32_e32 v168, 16, v127
	v_pk_fma_f32 v[124:125], v[124:125], v[124:125], v[170:171]
	v_and_b32_e32 v127, 0xffff0000, v112
	v_and_b32_e32 v126, 0xffff0000, v116
	v_pk_fma_f32 v[124:125], v[126:127], v[126:127], v[124:125]
	v_lshlrev_b32_e32 v127, 16, v113
	v_lshlrev_b32_e32 v126, 16, v117
	v_pk_fma_f32 v[124:125], v[126:127], v[126:127], v[124:125]
	v_and_b32_e32 v113, 0xffff0000, v113
	v_and_b32_e32 v112, 0xffff0000, v117
	v_pk_fma_f32 v[112:113], v[112:113], v[112:113], v[124:125]
	v_lshlrev_b32_e32 v117, 16, v114
	v_lshlrev_b32_e32 v116, 16, v118
	v_pk_fma_f32 v[112:113], v[116:117], v[116:117], v[112:113]
	v_and_b32_e32 v117, 0xffff0000, v114
	v_and_b32_e32 v116, 0xffff0000, v118
	v_and_b32_e32 v122, 0xffff0000, v119
	v_lshlrev_b32_e32 v125, 16, v115
	v_lshlrev_b32_e32 v124, 16, v119
	v_pk_fma_f32 v[112:113], v[116:117], v[116:117], v[112:113]
	v_and_b32_e32 v117, 0xffff0000, v109
	v_lshlrev_b32_e32 v116, 16, v109
	v_and_b32_e32 v119, 0xffff0000, v111
	v_lshlrev_b32_e32 v118, 16, v111
	v_lshlrev_b32_e32 v169, 16, v123
	v_and_b32_e32 v175, 0xffff0000, v123
	v_and_b32_e32 v123, 0xffff0000, v115
	v_pk_fma_f32 v[112:113], v[124:125], v[124:125], v[112:113]
	v_and_b32_e32 v115, 0xffff0000, v108
	v_lshlrev_b32_e32 v114, 16, v108
	v_pk_mul_f32 v[108:109], v[116:117], v[116:117]
	v_and_b32_e32 v117, 0xffff0000, v110
	v_lshlrev_b32_e32 v116, 16, v110
	v_pk_mul_f32 v[110:111], v[118:119], v[118:119]
	v_lshlrev_b32_e32 v118, 16, v104
	v_and_b32_e32 v104, 0xffff0000, v104
	v_pk_fma_f32 v[112:113], v[122:123], v[122:123], v[112:113]
	v_mul_f32_e32 v123, v104, v104
	v_lshlrev_b32_e32 v104, 16, v105
	v_mul_f32_e32 v125, v104, v104
	v_and_b32_e32 v104, 0xffff0000, v105
	v_pk_fma_f32 v[120:121], v[168:169], v[168:169], v[120:121]
	v_pk_mul_f32 v[114:115], v[114:115], v[114:115]
	v_mul_f32_e32 v105, v104, v104
	v_lshlrev_b32_e32 v104, 16, v106
	v_pk_fma_f32 v[120:121], v[174:175], v[174:175], v[120:121]
	v_mul_f32_e32 v119, v118, v118
	v_mul_f32_e32 v127, v104, v104
	v_and_b32_e32 v104, 0xffff0000, v106
	v_mov_b32_e32 v118, v114
	v_mul_f32_e32 v169, v104, v104
	v_lshlrev_b32_e32 v104, 16, v107
	v_pk_add_f32 v[118:119], v[118:119], v[120:121]
	v_mov_b32_e32 v122, v115
	v_mul_f32_e32 v171, v104, v104
	v_and_b32_e32 v104, 0xffff0000, v107
	v_pk_add_f32 v[114:115], v[122:123], v[118:119]
	v_mov_b32_e32 v124, v108
	v_pk_mul_f32 v[116:117], v[116:117], v[116:117]
	v_mul_f32_e32 v107, v104, v104
	v_pk_add_f32 v[114:115], v[124:125], v[114:115]
	v_mov_b32_e32 v104, v109
	v_pk_add_f32 v[104:105], v[104:105], v[114:115]
	v_mov_b32_e32 v126, v116
	v_pk_add_f32 v[104:105], v[126:127], v[104:105]
	v_mov_b32_e32 v168, v117
	v_pk_add_f32 v[104:105], v[168:169], v[104:105]
	v_mov_b32_e32 v170, v110
	v_pk_add_f32 v[104:105], v[170:171], v[104:105]
	v_mov_b32_e32 v106, v111
	v_pk_add_f32 v[168:169], v[106:107], v[104:105]
	v_and_b32_e32 v107, 0xffff0000, v101
	v_lshlrev_b32_e32 v106, 16, v101
	v_and_b32_e32 v105, 0xffff0000, v100
	v_lshlrev_b32_e32 v104, 16, v100
	v_pk_mul_f32 v[100:101], v[106:107], v[106:107]
	v_and_b32_e32 v107, 0xffff0000, v102
	v_lshlrev_b32_e32 v106, 16, v102
	v_and_b32_e32 v109, 0xffff0000, v103
	v_lshlrev_b32_e32 v108, 16, v103
	v_lshlrev_b32_e32 v102, 16, v96
	v_and_b32_e32 v96, 0xffff0000, v96
	v_pk_mul_f32 v[114:115], v[108:109], v[108:109]
	v_mul_f32_e32 v109, v96, v96
	v_lshlrev_b32_e32 v96, 16, v97
	v_mul_f32_e32 v111, v96, v96
	v_and_b32_e32 v96, 0xffff0000, v97
	v_mul_f32_e32 v97, v96, v96
	v_lshlrev_b32_e32 v96, 16, v98
	v_pk_mul_f32 v[104:105], v[104:105], v[104:105]
	v_mul_f32_e32 v117, v96, v96
	v_and_b32_e32 v96, 0xffff0000, v98
	v_mul_f32_e32 v103, v102, v102
	v_mul_f32_e32 v119, v96, v96
	v_lshlrev_b32_e32 v96, 16, v99
	v_mov_b32_e32 v102, v104
	v_mul_f32_e32 v121, v96, v96
	v_and_b32_e32 v96, 0xffff0000, v99
	v_pk_add_f32 v[98:99], v[102:103], v[112:113]
	v_mov_b32_e32 v108, v105
	v_pk_add_f32 v[98:99], v[108:109], v[98:99]
	v_mov_b32_e32 v110, v100
	v_pk_mul_f32 v[106:107], v[106:107], v[106:107]
	v_mul_f32_e32 v123, v96, v96
	v_pk_add_f32 v[98:99], v[110:111], v[98:99]
	v_mov_b32_e32 v96, v101
	v_pk_add_f32 v[96:97], v[96:97], v[98:99]
	v_mov_b32_e32 v116, v106
	v_pk_add_f32 v[96:97], v[116:117], v[96:97]
	v_mov_b32_e32 v118, v107
	v_pk_add_f32 v[112:113], v[118:119], v[96:97]
	ds_read_b128 v[96:99], v161
	ds_read_b128 v[100:103], v161 offset:4608
	ds_read_b128 v[104:107], v167 offset:18432
	ds_read_b128 v[108:111], v167 offset:23040
	v_mov_b32_e32 v120, v114
	v_pk_add_f32 v[112:113], v[120:121], v[112:113]
	v_mov_b32_e32 v122, v115
	v_pk_add_f32 v[170:171], v[122:123], v[112:113]
	s_xor_b64 s[12:13], s[4:5], -1
	s_waitcnt lgkmcnt(1)
;     ...
; #pragma unroll
;       for (int ks = 0; ks < 4; ++ks) {
;         bf16x8 af[2], bfr[2];
; #pragma unroll
;         for (int i = 0; i < 2; ++i) {
;           af[i] = *(const bf16x8*)(sA + (wm * 64 + i * 32) * LDT + fro + ks * 16);
;           bfr[i] = *(const bf16x8*)(sB + (wn * 64 + i * 32) * LDT + fro + ks * 16);
;         }
;         __builtin_amdgcn_s_setprio(1);
; #pragma unroll
;         for (int mi = 0; mi < 2; ++mi)
; #pragma unroll
;           for (int ni = 0; ni < 2; ++ni)
;             acc[mi][ni] = __builtin_amdgcn_mfma_f32_32x32x16_bf16(af[mi], bfr[ni], acc[mi][ni], 0, 0, 0);
;         __builtin_amdgcn_s_setprio(0);
;       }
	v_mfma_f32_32x32x16_bf16 v[48:63], v[96:99], v[104:107], v[48:63]
	s_waitcnt lgkmcnt(0)
	v_mfma_f32_32x32x16_bf16 v[32:47], v[96:99], v[108:111], v[32:47]
	v_mfma_f32_32x32x16_bf16 v[16:31], v[100:103], v[104:107], v[16:31]
	v_mfma_f32_32x32x16_bf16 v[0:15], v[100:103], v[108:111], v[0:15]
	ds_read_b128 v[96:99], v161 offset:32
	ds_read_b128 v[100:103], v161 offset:4640
	ds_read_b128 v[104:107], v167 offset:18464
	ds_read_b128 v[108:111], v167 offset:23072
	s_waitcnt lgkmcnt(1)
	v_mfma_f32_32x32x16_bf16 v[48:63], v[96:99], v[104:107], v[48:63]
	s_waitcnt lgkmcnt(0)
	v_mfma_f32_32x32x16_bf16 v[32:47], v[96:99], v[108:111], v[32:47]
	v_mfma_f32_32x32x16_bf16 v[16:31], v[100:103], v[104:107], v[16:31]
	v_mfma_f32_32x32x16_bf16 v[0:15], v[100:103], v[108:111], v[0:15]
	ds_read_b128 v[96:99], v161 offset:64
	ds_read_b128 v[100:103], v161 offset:4672
	ds_read_b128 v[104:107], v167 offset:18496
	ds_read_b128 v[108:111], v167 offset:23104
	s_waitcnt lgkmcnt(1)
	v_mfma_f32_32x32x16_bf16 v[48:63], v[96:99], v[104:107], v[48:63]
	s_waitcnt lgkmcnt(0)
	v_mfma_f32_32x32x16_bf16 v[32:47], v[96:99], v[108:111], v[32:47]
	v_mfma_f32_32x32x16_bf16 v[16:31], v[100:103], v[104:107], v[16:31]
	v_mfma_f32_32x32x16_bf16 v[0:15], v[100:103], v[108:111], v[0:15]
	ds_read_b128 v[96:99], v161 offset:96
	ds_read_b128 v[100:103], v161 offset:4704
	ds_read_b128 v[104:107], v167 offset:18528
	ds_read_b128 v[108:111], v167 offset:23136
	s_waitcnt lgkmcnt(1)
	v_mfma_f32_32x32x16_bf16 v[48:63], v[96:99], v[104:107], v[48:63]
	s_waitcnt lgkmcnt(0)
	v_mfma_f32_32x32x16_bf16 v[32:47], v[96:99], v[108:111], v[32:47]
	v_mfma_f32_32x32x16_bf16 v[16:31], v[100:103], v[104:107], v[16:31]
	v_mfma_f32_32x32x16_bf16 v[0:15], v[100:103], v[108:111], v[0:15]
	s_setprio 0
	s_waitcnt vmcnt(0)
	v_mov_b64_e32 v[96:97], v[156:157]
	v_mov_b64_e32 v[100:101], v[148:149]
	v_mov_b64_e32 v[104:105], v[144:145]
	v_mov_b64_e32 v[108:109], v[152:153]
	v_mov_b64_e32 v[112:113], v[140:141]
	v_mov_b64_e32 v[116:117], v[132:133]
	v_mov_b64_e32 v[120:121], v[128:129]
	v_mov_b64_e32 v[124:125], v[136:137]
	s_mov_b64 s[4:5], 0
	s_and_b64 vcc, exec, s[12:13]
	v_mov_b64_e32 v[98:99], v[158:159]
	v_mov_b64_e32 v[102:103], v[150:151]
	v_mov_b64_e32 v[106:107], v[146:147]
	v_mov_b64_e32 v[110:111], v[154:155]
	v_mov_b64_e32 v[114:115], v[142:143]
	v_mov_b64_e32 v[118:119], v[134:135]
	v_mov_b64_e32 v[122:123], v[130:131]
	v_mov_b64_e32 v[126:127], v[138:139]
	s_cbranch_vccnz .LBB0_737

; DEV float bf2f(u16 h) { return __uint_as_float(((unsigned)h) << 16); }
;     ...
;     for (int d = 0; d < DEPTH; ++d) {
;       __syncthreads();
; #pragma unroll
;       for (int i = 0; i < 4; ++i) {
;         *(bf16x8*)(sA + (srow + 32 * i) * LDT + scol) = ra[d][i];
;         *(bf16x8*)(sB + (srow + 32 * i) * LDT + scol) = rb[d][i];
;         if (SS) {
;           bf16x8 v = (SS == 1) ? ra[d][i] : rb[d][i];
; #pragma unroll
;           for (int j = 0; j < 8; ++j) {
;             float f = bf2f((u16)v[j]);
;             ssq[i] += f * f;
;           }
;         }
;       }
;       __syncthreads();
;       if (kt + d + DEPTH < nk) {
; #pragma unroll
;         for (int i = 0; i < 4; ++i) {
;           ra[d][i] = *(const bf16x8*)(ap + (size_t)(32 * i) * lda);
;           rb[d][i] = *(const bf16x8*)(bp + (size_t)(32 * i) * ldb);
;         }
;         ap += 64;
;         bp += 64;
;       }
; #pragma unroll
;       for (int ks = 0; ks < 4; ++ks) {
;         bf16x8 af[2], bfr[2];
; #pragma unroll
;         for (int i = 0; i < 2; ++i) {
;           af[i] = *(const bf16x8*)(sA + (wm * 64 + i * 32) * LDT + fro + ks * 16);
;           bfr[i] = *(const bf16x8*)(sB + (wn * 64 + i * 32) * LDT + fro + ks * 16);
;         }
;         __builtin_amdgcn_s_setprio(1);
; #pragma unroll
;         for (int mi = 0; mi < 2; ++mi)
; #pragma unroll
;           for (int ni = 0; ni < 2; ++ni)
;             acc[mi][ni] = __builtin_amdgcn_mfma_f32_32x32x16_bf16(af[mi], bfr[ni], acc[mi][ni], 0, 0, 0);
;         __builtin_amdgcn_s_setprio(0);
;       }
.LBB0_735:
	s_setprio 1
	ds_read_b128 v[144:147], v161
	ds_read_b128 v[148:151], v161 offset:4608
	ds_read_b128 v[152:155], v167 offset:18432
	ds_read_b128 v[156:159], v167 offset:23040
	s_waitcnt lgkmcnt(1)
	v_mfma_f32_32x32x16_bf16 v[48:63], v[144:147], v[152:155], v[48:63]
	s_waitcnt lgkmcnt(0)
	v_mfma_f32_32x32x16_bf16 v[32:47], v[144:147], v[156:159], v[32:47]
	v_mfma_f32_32x32x16_bf16 v[16:31], v[148:151], v[152:155], v[16:31]
	v_mfma_f32_32x32x16_bf16 v[0:15], v[148:151], v[156:159], v[0:15]
	ds_read_b128 v[144:147], v161 offset:32
	ds_read_b128 v[148:151], v161 offset:4640
	ds_read_b128 v[152:155], v167 offset:18464
	ds_read_b128 v[156:159], v167 offset:23072
	s_waitcnt lgkmcnt(1)
	v_mfma_f32_32x32x16_bf16 v[48:63], v[144:147], v[152:155], v[48:63]
	s_waitcnt lgkmcnt(0)
	v_mfma_f32_32x32x16_bf16 v[32:47], v[144:147], v[156:159], v[32:47]
	v_mfma_f32_32x32x16_bf16 v[16:31], v[148:151], v[152:155], v[16:31]
	v_mfma_f32_32x32x16_bf16 v[0:15], v[148:151], v[156:159], v[0:15]
	ds_read_b128 v[144:147], v161 offset:64
	ds_read_b128 v[148:151], v161 offset:4672
	ds_read_b128 v[152:155], v167 offset:18496
	ds_read_b128 v[156:159], v167 offset:23104
	s_waitcnt lgkmcnt(1)
	v_mfma_f32_32x32x16_bf16 v[48:63], v[144:147], v[152:155], v[48:63]
	s_waitcnt lgkmcnt(0)
	v_mfma_f32_32x32x16_bf16 v[32:47], v[144:147], v[156:159], v[32:47]
	v_mfma_f32_32x32x16_bf16 v[16:31], v[148:151], v[152:155], v[16:31]
	v_mfma_f32_32x32x16_bf16 v[0:15], v[148:151], v[156:159], v[0:15]
	ds_read_b128 v[144:147], v161 offset:96
	ds_read_b128 v[148:151], v161 offset:4704
	ds_read_b128 v[152:155], v167 offset:18528
	ds_read_b128 v[156:159], v167 offset:23136
	s_waitcnt lgkmcnt(1)
	v_mfma_f32_32x32x16_bf16 v[48:63], v[144:147], v[152:155], v[48:63]
	s_waitcnt lgkmcnt(0)
	v_mfma_f32_32x32x16_bf16 v[32:47], v[144:147], v[156:159], v[32:47]
	v_mfma_f32_32x32x16_bf16 v[16:31], v[148:151], v[152:155], v[16:31]
	v_mfma_f32_32x32x16_bf16 v[0:15], v[148:151], v[156:159], v[0:15]
	s_setprio 0
	s_andn2_b64 vcc, exec, s[4:5]
	s_barrier
	ds_write_b128 v166, v[68:71]
	ds_write_b128 v166, v[108:111] offset:18432
	ds_write_b128 v166, v[76:79] offset:4608
	ds_write_b128 v166, v[104:107] offset:23040
	ds_write_b128 v166, v[84:87] offset:9216
	ds_write_b128 v166, v[100:103] offset:27648
	ds_write_b128 v166, v[92:95] offset:13824
	s_waitcnt vmcnt(0)
	ds_write_b128 v166, v[96:99] offset:32256
	s_waitcnt lgkmcnt(0)
	s_barrier
	s_cbranch_vccz .LBB0_730
	v_mov_b64_e32 v[158:159], v[98:99]
	v_mov_b64_e32 v[150:151], v[102:103]
	v_mov_b64_e32 v[146:147], v[106:107]
	v_mov_b64_e32 v[154:155], v[110:111]
	v_mov_b64_e32 v[156:157], v[96:97]
	v_mov_b64_e32 v[148:149], v[100:101]
	v_mov_b64_e32 v[144:145], v[104:105]
	v_mov_b64_e32 v[152:153], v[108:109]
	s_branch .LBB0_731

; DEV float sigmoidf_(float x) { return 1.0f / (1.0f + __expf(-x)); }
; DEV void gemm_gates(f32x16 (&acc)[2][4], const u16* __restrict__ A, const u16* __restrict__ B0, const u16* __restrict__ B1,
;                     unsigned char* smem) {
;     ...
; #pragma unroll 2
;     for (int ks = 0; ks < 4; ++ks) {
;       bf16x8 af[2], bfr[4];
; #pragma unroll
;       for (int i = 0; i < 2; ++i) af[i] = *(const bf16x8*)(sA + (wm * 64 + i * 32) * LDT + fro + ks * 16);
; #pragma unroll
;       for (int i = 0; i < 4; ++i)
;         bfr[i] = *(const bf16x8*)(sB + ((i >> 1) * 128 + wn * 64 + (i & 1) * 32) * LDT + fro + ks * 16);
;       __builtin_amdgcn_s_setprio(1);
; #pragma unroll
;       for (int mi = 0; mi < 2; ++mi)
; #pragma unroll
;         for (int ni = 0; ni < 4; ++ni)
;           acc[mi][ni] = __builtin_amdgcn_mfma_f32_32x32x16_bf16(af[mi], bfr[ni], acc[mi][ni], 0, 0, 0);
;       __builtin_amdgcn_s_setprio(0);
;     }
; DEV void phase_p5(const Params& p, int l, unsigned char* smem) {
;     ...
; #pragma unroll
;       for (int a_ = 0; a_ < 2; ++a_)
; #pragma unroll
;         for (int b_ = 0; b_ < 2; ++b_) {
; #pragma unroll
;           for (int r = 0; r < 8; ++r)
;             sG[((a_ * 2 + b_) * 8 + r) * 256 + tid] = pk2bf(sigmoidf_(g[a_][2 + b_][2 * r]), sigmoidf_(g[a_][2 + b_][2 * r + 1]));
;           __builtin_amdgcn_sched_barrier(0);
.LBB0_1309:
	s_setprio 1
	v_add_u32_e32 v210, s36, v183
	v_add_u32_e32 v211, s36, v184
	ds_read_b128 v[186:189], v210
	ds_read_b128 v[190:193], v210 offset:4608
	ds_read_b128 v[194:197], v211
	ds_read_b128 v[198:201], v211 offset:4608
	ds_read_b128 v[202:205], v211 offset:18432
	ds_read_b128 v[206:209], v211 offset:23040
	s_waitcnt lgkmcnt(3)
	v_mfma_f32_32x32x16_bf16 v[48:63], v[186:189], v[194:197], v[48:63]
	s_waitcnt lgkmcnt(2)
	v_mfma_f32_32x32x16_bf16 v[32:47], v[186:189], v[198:201], v[32:47]
	s_waitcnt lgkmcnt(1)
	v_mfma_f32_32x32x16_bf16 v[112:127], v[186:189], v[202:205], v[112:127]
	s_waitcnt lgkmcnt(0)
	v_mfma_f32_32x32x16_bf16 v[96:111], v[186:189], v[206:209], v[96:111]
	v_mfma_f32_32x32x16_bf16 v[16:31], v[190:193], v[194:197], v[16:31]
	v_mfma_f32_32x32x16_bf16 v[0:15], v[190:193], v[198:201], v[0:15]
	v_mfma_f32_32x32x16_bf16 v[80:95], v[190:193], v[202:205], v[80:95]
	v_mfma_f32_32x32x16_bf16 v[64:79], v[190:193], v[206:209], v[64:79]
	ds_read_b128 v[186:189], v210 offset:32
	ds_read_b128 v[190:193], v210 offset:4640
	ds_read_b128 v[194:197], v211 offset:32
	ds_read_b128 v[198:201], v211 offset:4640
	ds_read_b128 v[202:205], v211 offset:18464
	ds_read_b128 v[206:209], v211 offset:23072
	s_waitcnt lgkmcnt(3)
	v_mfma_f32_32x32x16_bf16 v[48:63], v[186:189], v[194:197], v[48:63]
	s_waitcnt lgkmcnt(2)
	v_mfma_f32_32x32x16_bf16 v[32:47], v[186:189], v[198:201], v[32:47]
	s_waitcnt lgkmcnt(1)
	v_mfma_f32_32x32x16_bf16 v[112:127], v[186:189], v[202:205], v[112:127]
	s_waitcnt lgkmcnt(0)
	v_mfma_f32_32x32x16_bf16 v[96:111], v[186:189], v[206:209], v[96:111]
	v_mfma_f32_32x32x16_bf16 v[16:31], v[190:193], v[194:197], v[16:31]
	v_mfma_f32_32x32x16_bf16 v[0:15], v[190:193], v[198:201], v[0:15]
	v_mfma_f32_32x32x16_bf16 v[80:95], v[190:193], v[202:205], v[80:95]
	v_mfma_f32_32x32x16_bf16 v[64:79], v[190:193], v[206:209], v[64:79]
	s_setprio 0
	s_add_i32 s36, s36, 64
	s_cmpk_eq_i32 s36, 0x80
	s_cbranch_scc0 .LBB0_1309
	s_add_i32 s21, s21, 1
	s_cmp_eq_u32 s21, 16
	s_cbranch_scc0 .LBB0_1306
	v_mul_f32_e32 v112, 0xbfb8aa3b, v112
	v_mul_f32_e32 v113, 0xbfb8aa3b, v113
	v_exp_f32_e32 v112, v112
	v_exp_f32_e32 v113, v113
	v_lshlrev_b32_e32 v248, 2, v182
	s_barrier
	s_lshl_b64 s[36:37], s[0:1], 1
	s_add_u32 s36, s8, s36
	s_addc_u32 s37, s9, s37
	s_lshl_b32 s38, s20, 1
	s_add_u32 s38, s14, s38
	s_addc_u32 s39, s15, 0
	v_ashrrev_i32_e32 v216, 3, v232
	v_ashrrev_i32_e32 v217, 31, v216
	v_lshlrev_b64 v[216:217], 11, v[216:217]
	v_lshlrev_b32_e32 v218, 4, v232
	v_and_b32_e32 v218, 0x70, v218
	v_mov_b32_e32 v219, 0
	v_lshl_add_u64 v[220:221], s[36:37], 0, v[216:217]
	v_lshl_add_u64 v[220:221], v[220:221], 0, v[218:219]
	v_lshl_add_u64 v[222:223], s[38:39], 0, v[216:217]
	v_lshl_add_u64 v[222:223], v[222:223], 0, v[218:219]
	global_load_dwordx4 v[184:187], v[220:221], off
	global_load_dwordx4 v[188:191], v[222:223], off
	v_add_co_u32_e32 v216, vcc, s35, v220
	s_nop 1
	v_addc_co_u32_e32 v217, vcc, 0, v221, vcc
	global_load_dwordx4 v[192:195], v[216:217], off
	v_add_co_u32_e32 v218, vcc, s35, v222
	s_nop 1
	v_addc_co_u32_e32 v219, vcc, 0, v223, vcc
	global_load_dwordx4 v[196:199], v[218:219], off
	v_add_co_u32_e32 v216, vcc, s33, v220
	s_nop 1
	v_addc_co_u32_e32 v217, vcc, 0, v221, vcc
	global_load_dwordx4 v[200:203], v[216:217], off
	v_add_co_u32_e32 v218, vcc, s33, v222
	s_nop 1
	v_addc_co_u32_e32 v219, vcc, 0, v223, vcc
	global_load_dwordx4 v[204:207], v[218:219], off
	v_add_co_u32_e32 v216, vcc, s40, v220
	s_nop 1
	v_addc_co_u32_e32 v217, vcc, 0, v221, vcc
	global_load_dwordx4 v[208:211], v[216:217], off
	v_add_co_u32_e32 v218, vcc, s40, v222
	s_nop 1
	v_addc_co_u32_e32 v219, vcc, 0, v223, vcc
	global_load_dwordx4 v[212:215], v[218:219], off
	v_pk_add_f32 v[112:113], v[112:113], 1.0 op_sel_hi:[1,0]
	s_waitcnt vmcnt(10)
	v_add_u32_e32 v249, 0x9400, v248
	s_waitcnt vmcnt(9)
	v_rcp_f32_e32 v113, v113
	s_nop 0
	s_nop 0
	v_rcp_f32_e32 v112, v112
	s_nop 0
	v_cvt_pk_bf16_f32 v128, v112, v113
	v_mul_f32_e32 v112, 0xbfb8aa3b, v114
	v_mul_f32_e32 v113, 0xbfb8aa3b, v115
	v_exp_f32_e32 v112, v112
	v_exp_f32_e32 v113, v113
	s_nop 0
	v_pk_add_f32 v[112:113], v[112:113], 1.0 op_sel_hi:[1,0]
	s_nop 0
	s_nop 0
	v_rcp_f32_e32 v113, v113
	s_nop 0
	s_nop 0
	v_rcp_f32_e32 v112, v112
	s_nop 0
	v_cvt_pk_bf16_f32 v112, v112, v113
	ds_write2st64_b32 v248, v128, v112 offset0:148 offset1:152
	v_mul_f32_e32 v112, 0xbfb8aa3b, v116
	v_mul_f32_e32 v113, 0xbfb8aa3b, v117
	v_exp_f32_e32 v112, v112
	v_exp_f32_e32 v113, v113
	s_nop 0
	v_pk_add_f32 v[112:113], v[112:113], 1.0 op_sel_hi:[1,0]
	s_nop 0
	s_nop 0
	v_rcp_f32_e32 v113, v113
	s_nop 0
	s_nop 0
	v_rcp_f32_e32 v112, v112
	s_nop 0
	v_cvt_pk_bf16_f32 v114, v112, v113
	v_mul_f32_e32 v112, 0xbfb8aa3b, v118
	v_mul_f32_e32 v113, 0xbfb8aa3b, v119
	v_exp_f32_e32 v112, v112
	v_exp_f32_e32 v113, v113
	s_nop 0
	v_pk_add_f32 v[112:113], v[112:113], 1.0 op_sel_hi:[1,0]
	s_nop 0
	s_nop 0
	v_rcp_f32_e32 v113, v113
	s_nop 0
	s_nop 0
	v_rcp_f32_e32 v112, v112
	s_nop 0
	v_cvt_pk_bf16_f32 v112, v112, v113
	ds_write2st64_b32 v248, v114, v112 offset0:156 offset1:160
	v_mul_f32_e32 v112, 0xbfb8aa3b, v120
	v_mul_f32_e32 v113, 0xbfb8aa3b, v121
	v_exp_f32_e32 v112, v112
	v_exp_f32_e32 v113, v113
	s_nop 0
	v_pk_add_f32 v[112:113], v[112:113], 1.0 op_sel_hi:[1,0]
	s_nop 0
	s_nop 0
	v_rcp_f32_e32 v113, v113
	s_nop 0
	s_nop 0
	v_rcp_f32_e32 v112, v112
	s_nop 0
	v_cvt_pk_bf16_f32 v114, v112, v113
	v_mul_f32_e32 v112, 0xbfb8aa3b, v122
	v_mul_f32_e32 v113, 0xbfb8aa3b, v123
	v_exp_f32_e32 v112, v112
	v_exp_f32_e32 v113, v113
	s_nop 0
	v_pk_add_f32 v[112:113], v[112:113], 1.0 op_sel_hi:[1,0]
	s_nop 0
	s_nop 0
	v_rcp_f32_e32 v113, v113
	s_nop 0
	s_nop 0
; DEV float sigmoidf_(float x) { return 1.0f / (1.0f + __expf(-x)); }
; DEV void phase_p5(const Params& p, int l, unsigned char* smem) {
;     ...
; #pragma unroll
;       for (int a_ = 0; a_ < 2; ++a_)
; #pragma unroll
;         for (int b_ = 0; b_ < 2; ++b_) {
; #pragma unroll
;           for (int r = 0; r < 8; ++r)
;             sG[((a_ * 2 + b_) * 8 + r) * 256 + tid] = pk2bf(sigmoidf_(g[a_][2 + b_][2 * r]), sigmoidf_(g[a_][2 + b_][2 * r + 1]));
;           __builtin_amdgcn_sched_barrier(0);
	v_rcp_f32_e32 v112, v112
	s_nop 0
	v_cvt_pk_bf16_f32 v112, v112, v113
	ds_write2st64_b32 v248, v114, v112 offset0:164 offset1:168
	v_mul_f32_e32 v112, 0xbfb8aa3b, v124
	v_mul_f32_e32 v113, 0xbfb8aa3b, v125
	v_exp_f32_e32 v112, v112
	v_exp_f32_e32 v113, v113
	s_nop 0
	v_pk_add_f32 v[112:113], v[112:113], 1.0 op_sel_hi:[1,0]
	s_nop 0
	s_nop 0
	v_rcp_f32_e32 v113, v113
	s_nop 0
	s_nop 0
	v_rcp_f32_e32 v112, v112
	s_nop 0
	v_cvt_pk_bf16_f32 v114, v112, v113
	v_mul_f32_e32 v112, 0xbfb8aa3b, v126
	v_mul_f32_e32 v113, 0xbfb8aa3b, v127
	v_exp_f32_e32 v112, v112
	v_exp_f32_e32 v113, v113
	s_nop 0
	v_pk_add_f32 v[112:113], v[112:113], 1.0 op_sel_hi:[1,0]
	s_nop 0
	s_nop 0
	v_rcp_f32_e32 v113, v113
	s_nop 0
	s_nop 0
	v_rcp_f32_e32 v112, v112
	s_nop 0
	v_cvt_pk_bf16_f32 v112, v112, v113
	ds_write2st64_b32 v248, v114, v112 offset0:172 offset1:176
	v_mul_f32_e32 v96, 0xbfb8aa3b, v96
	v_mul_f32_e32 v97, 0xbfb8aa3b, v97
	v_exp_f32_e32 v96, v96
	v_exp_f32_e32 v97, v97
	s_nop 0
	v_pk_add_f32 v[96:97], v[96:97], 1.0 op_sel_hi:[1,0]
	s_nop 0
	s_nop 0
	v_rcp_f32_e32 v97, v97
	s_nop 0
	s_nop 0
	v_rcp_f32_e32 v96, v96
	s_nop 0
	v_cvt_pk_bf16_f32 v112, v96, v97
	v_mul_f32_e32 v96, 0xbfb8aa3b, v98
	v_mul_f32_e32 v97, 0xbfb8aa3b, v99
	v_exp_f32_e32 v96, v96
	v_exp_f32_e32 v97, v97
	s_nop 0
	v_pk_add_f32 v[96:97], v[96:97], 1.0 op_sel_hi:[1,0]
	s_nop 0
	s_nop 0
	v_rcp_f32_e32 v97, v97
	s_nop 0
	s_nop 0
	v_rcp_f32_e32 v96, v96
	s_nop 0
	v_cvt_pk_bf16_f32 v96, v96, v97
	ds_write2st64_b32 v248, v112, v96 offset0:180 offset1:184
	v_mul_f32_e32 v96, 0xbfb8aa3b, v100
	v_mul_f32_e32 v97, 0xbfb8aa3b, v101
	v_exp_f32_e32 v96, v96
	v_exp_f32_e32 v97, v97
	s_nop 0
	v_pk_add_f32 v[96:97], v[96:97], 1.0 op_sel_hi:[1,0]
	s_nop 0
	s_nop 0
	v_rcp_f32_e32 v97, v97
	s_nop 0
	s_nop 0
	v_rcp_f32_e32 v96, v96
	s_nop 0
	v_cvt_pk_bf16_f32 v98, v96, v97
	v_mul_f32_e32 v96, 0xbfb8aa3b, v102
	v_mul_f32_e32 v97, 0xbfb8aa3b, v103
	v_exp_f32_e32 v96, v96
	v_exp_f32_e32 v97, v97
	s_nop 0
	v_pk_add_f32 v[96:97], v[96:97], 1.0 op_sel_hi:[1,0]
	s_nop 0
	s_nop 0
	v_rcp_f32_e32 v97, v97
	s_nop 0
	s_nop 0
	v_rcp_f32_e32 v96, v96
	s_nop 0
	v_cvt_pk_bf16_f32 v96, v96, v97
	ds_write2st64_b32 v248, v98, v96 offset0:188 offset1:192
	v_mul_f32_e32 v96, 0xbfb8aa3b, v104
	v_mul_f32_e32 v97, 0xbfb8aa3b, v105
	v_exp_f32_e32 v96, v96
	v_exp_f32_e32 v97, v97
	s_nop 0
	v_pk_add_f32 v[96:97], v[96:97], 1.0 op_sel_hi:[1,0]
	s_nop 0
	s_nop 0
	v_rcp_f32_e32 v97, v97
	s_nop 0
	s_nop 0
	v_rcp_f32_e32 v96, v96
	s_nop 0
	v_cvt_pk_bf16_f32 v98, v96, v97
	v_mul_f32_e32 v96, 0xbfb8aa3b, v106
	v_mul_f32_e32 v97, 0xbfb8aa3b, v107
	v_exp_f32_e32 v96, v96
	v_exp_f32_e32 v97, v97
	s_nop 0
	v_pk_add_f32 v[96:97], v[96:97], 1.0 op_sel_hi:[1,0]
	s_nop 0
	s_nop 0
	v_rcp_f32_e32 v97, v97
	s_nop 0
	s_nop 0
	v_rcp_f32_e32 v96, v96
	s_nop 0
	v_cvt_pk_bf16_f32 v96, v96, v97
	ds_write2st64_b32 v248, v98, v96 offset0:196 offset1:200
	v_mul_f32_e32 v96, 0xbfb8aa3b, v108
	v_mul_f32_e32 v97, 0xbfb8aa3b, v109
	v_exp_f32_e32 v96, v96
	v_exp_f32_e32 v97, v97
	s_nop 0
	v_pk_add_f32 v[96:97], v[96:97], 1.0 op_sel_hi:[1,0]
	s_nop 0
	s_nop 0
	v_rcp_f32_e32 v97, v97
	s_nop 0
	s_nop 0
	v_rcp_f32_e32 v96, v96
	s_nop 0
	v_cvt_pk_bf16_f32 v98, v96, v97
	v_mul_f32_e32 v96, 0xbfb8aa3b, v110
	v_mul_f32_e32 v97, 0xbfb8aa3b, v111
	v_exp_f32_e32 v96, v96
	v_exp_f32_e32 v97, v97
	s_nop 0
	v_pk_add_f32 v[96:97], v[96:97], 1.0 op_sel_hi:[1,0]
	s_nop 0
	s_nop 0
	v_rcp_f32_e32 v97, v97
	s_nop 0
	s_nop 0
	v_rcp_f32_e32 v96, v96
	s_nop 0
	v_cvt_pk_bf16_f32 v96, v96, v97
	ds_write2st64_b32 v248, v98, v96 offset0:204 offset1:208
	v_mul_f32_e32 v80, 0xbfb8aa3b, v80
	v_mul_f32_e32 v81, 0xbfb8aa3b, v81
	v_exp_f32_e32 v80, v80
	v_exp_f32_e32 v81, v81
	s_nop 0
	v_pk_add_f32 v[80:81], v[80:81], 1.0 op_sel_hi:[1,0]
	s_nop 0
	s_nop 0
	v_rcp_f32_e32 v81, v81
	s_nop 0
	s_nop 0
	v_rcp_f32_e32 v80, v80
	s_nop 0
	v_cvt_pk_bf16_f32 v96, v80, v81
	v_mul_f32_e32 v80, 0xbfb8aa3b, v82
	v_mul_f32_e32 v81, 0xbfb8aa3b, v83
	v_exp_f32_e32 v80, v80
	v_exp_f32_e32 v81, v81
	s_nop 0
	v_pk_add_f32 v[80:81], v[80:81], 1.0 op_sel_hi:[1,0]
	s_nop 0
	s_nop 0
	v_rcp_f32_e32 v81, v81
	s_nop 0
	s_nop 0
	v_rcp_f32_e32 v80, v80
	s_nop 0
	v_cvt_pk_bf16_f32 v80, v80, v81
	ds_write2st64_b32 v248, v96, v80 offset0:212 offset1:216
	v_mul_f32_e32 v80, 0xbfb8aa3b, v84
	v_mul_f32_e32 v81, 0xbfb8aa3b, v85
	v_exp_f32_e32 v80, v80
	v_exp_f32_e32 v81, v81
	s_nop 0
	v_pk_add_f32 v[80:81], v[80:81], 1.0 op_sel_hi:[1,0]
	s_nop 0
	s_nop 0
	v_rcp_f32_e32 v81, v81
	s_nop 0
	s_nop 0
	v_rcp_f32_e32 v80, v80
	s_nop 0
	v_cvt_pk_bf16_f32 v82, v80, v81
	v_mul_f32_e32 v80, 0xbfb8aa3b, v86
	v_mul_f32_e32 v81, 0xbfb8aa3b, v87
	v_exp_f32_e32 v80, v80
	v_exp_f32_e32 v81, v81
	s_nop 0
	v_pk_add_f32 v[80:81], v[80:81], 1.0 op_sel_hi:[1,0]
	s_nop 0
	s_nop 0
	v_rcp_f32_e32 v81, v81
	s_nop 0
	s_nop 0
	v_rcp_f32_e32 v80, v80
	s_nop 0
	v_cvt_pk_bf16_f32 v80, v80, v81
	ds_write2st64_b32 v248, v82, v80 offset0:220 offset1:224
	v_mul_f32_e32 v80, 0xbfb8aa3b, v88
	v_mul_f32_e32 v81, 0xbfb8aa3b, v89
	v_exp_f32_e32 v80, v80
	v_exp_f32_e32 v81, v81
	s_nop 0
	v_pk_add_f32 v[80:81], v[80:81], 1.0 op_sel_hi:[1,0]
	s_nop 0
	s_nop 0
	v_rcp_f32_e32 v81, v81
	s_nop 0
	s_nop 0
	v_rcp_f32_e32 v80, v80
	s_nop 0
	v_cvt_pk_bf16_f32 v82, v80, v81
	v_mul_f32_e32 v80, 0xbfb8aa3b, v90
	v_mul_f32_e32 v81, 0xbfb8aa3b, v91
	v_exp_f32_e32 v80, v80
	v_exp_f32_e32 v81, v81
	s_nop 0
	v_pk_add_f32 v[80:81], v[80:81], 1.0 op_sel_hi:[1,0]
	s_nop 0
	s_nop 0
	v_rcp_f32_e32 v81, v81
	s_nop 0
	s_nop 0
	v_rcp_f32_e32 v80, v80
	s_nop 0
	v_cvt_pk_bf16_f32 v80, v80, v81
	ds_write2st64_b32 v248, v82, v80 offset0:228 offset1:232
	v_mul_f32_e32 v80, 0xbfb8aa3b, v92
; DEV float sigmoidf_(float x) { return 1.0f / (1.0f + __expf(-x)); }
;   u16* sA = (u16*)smem;
;   u16* sB = sA + 128 * LDT;
;   float* ss = (float*)(sB + 128 * LDT);
;   const int tid = TIDX(), lane = tid & 63, w = tid >> 6, wm = w >> 1, wn = w & 1;
;   const int srow = tid >> 3, scol = (tid & 7) * 8;
;   const u16* ap = A + (size_t)srow * lda + scol;
;   const u16* bp = B + (size_t)srow * ldb + scol;
; DEV void phase_p5(const Params& p, int l, unsigned char* smem) {
;     ...
; #pragma unroll
;       for (int a_ = 0; a_ < 2; ++a_)
; #pragma unroll
;         for (int b_ = 0; b_ < 2; ++b_) {
; #pragma unroll
;           for (int r = 0; r < 8; ++r)
;             sG[((a_ * 2 + b_) * 8 + r) * 256 + tid] = pk2bf(sigmoidf_(g[a_][2 + b_][2 * r]), sigmoidf_(g[a_][2 + b_][2 * r + 1]));
;           __builtin_amdgcn_sched_barrier(0);
	v_mul_f32_e32 v81, 0xbfb8aa3b, v93
	v_exp_f32_e32 v80, v80
	v_exp_f32_e32 v81, v81
	s_nop 0
	v_pk_add_f32 v[80:81], v[80:81], 1.0 op_sel_hi:[1,0]
	s_nop 0
	s_nop 0
	v_rcp_f32_e32 v81, v81
	s_nop 0
	s_nop 0
	v_rcp_f32_e32 v80, v80
	s_nop 0
	v_cvt_pk_bf16_f32 v82, v80, v81
	v_mul_f32_e32 v80, 0xbfb8aa3b, v94
	v_mul_f32_e32 v81, 0xbfb8aa3b, v95
	v_exp_f32_e32 v80, v80
	v_exp_f32_e32 v81, v81
	s_nop 0
	v_pk_add_f32 v[80:81], v[80:81], 1.0 op_sel_hi:[1,0]
	s_nop 0
	s_nop 0
	v_rcp_f32_e32 v81, v81
	s_nop 0
	s_nop 0
	v_rcp_f32_e32 v80, v80
	s_nop 0
	v_cvt_pk_bf16_f32 v80, v80, v81
	ds_write2st64_b32 v248, v82, v80 offset0:236 offset1:240
	v_mul_f32_e32 v64, 0xbfb8aa3b, v64
	v_mul_f32_e32 v65, 0xbfb8aa3b, v65
	v_exp_f32_e32 v64, v64
	v_exp_f32_e32 v65, v65
	s_nop 0
	v_pk_add_f32 v[64:65], v[64:65], 1.0 op_sel_hi:[1,0]
	s_nop 0
	s_nop 0
	v_rcp_f32_e32 v65, v65
	s_nop 0
	s_nop 0
	v_rcp_f32_e32 v64, v64
	s_nop 0
	v_cvt_pk_bf16_f32 v80, v64, v65
	v_mul_f32_e32 v64, 0xbfb8aa3b, v66
	v_mul_f32_e32 v65, 0xbfb8aa3b, v67
	v_exp_f32_e32 v64, v64
	v_exp_f32_e32 v65, v65
	s_nop 0
	v_pk_add_f32 v[64:65], v[64:65], 1.0 op_sel_hi:[1,0]
	s_nop 0
	s_nop 0
	v_rcp_f32_e32 v65, v65
	s_nop 0
	s_nop 0
	v_rcp_f32_e32 v64, v64
	s_nop 0
	v_cvt_pk_bf16_f32 v64, v64, v65
	ds_write2st64_b32 v248, v80, v64 offset0:244 offset1:248
	v_mul_f32_e32 v64, 0xbfb8aa3b, v68
	v_mul_f32_e32 v65, 0xbfb8aa3b, v69
	v_exp_f32_e32 v64, v64
	v_exp_f32_e32 v65, v65
	s_nop 0
	v_pk_add_f32 v[64:65], v[64:65], 1.0 op_sel_hi:[1,0]
	s_nop 0
	s_nop 0
	v_rcp_f32_e32 v65, v65
	s_nop 0
	s_nop 0
	v_rcp_f32_e32 v64, v64
	s_nop 0
	v_cvt_pk_bf16_f32 v64, v64, v65
	ds_write_b32 v248, v64 offset:64512
	v_mul_f32_e32 v64, 0xbfb8aa3b, v70
	v_mul_f32_e32 v65, 0xbfb8aa3b, v71
	v_exp_f32_e32 v64, v64
	v_exp_f32_e32 v65, v65
	s_nop 0
	v_pk_add_f32 v[64:65], v[64:65], 1.0 op_sel_hi:[1,0]
	s_nop 0
	s_nop 0
	v_rcp_f32_e32 v65, v65
	s_nop 0
	s_nop 0
	v_rcp_f32_e32 v64, v64
	s_nop 0
	v_cvt_pk_bf16_f32 v66, v64, v65
	v_mul_f32_e32 v64, 0xbfb8aa3b, v72
	v_mul_f32_e32 v65, 0xbfb8aa3b, v73
	v_exp_f32_e32 v64, v64
	v_exp_f32_e32 v65, v65
	s_nop 0
	v_pk_add_f32 v[64:65], v[64:65], 1.0 op_sel_hi:[1,0]
	s_nop 0
	s_nop 0
	v_rcp_f32_e32 v65, v65
	s_nop 0
	s_nop 0
	v_rcp_f32_e32 v64, v64
	s_nop 0
	v_cvt_pk_bf16_f32 v64, v64, v65
	ds_write2st64_b32 v249, v66, v64 offset0:108 offset1:112
	v_mul_f32_e32 v64, 0xbfb8aa3b, v74
	v_mul_f32_e32 v65, 0xbfb8aa3b, v75
	v_exp_f32_e32 v64, v64
	v_exp_f32_e32 v65, v65
	s_nop 0
	v_pk_add_f32 v[64:65], v[64:65], 1.0 op_sel_hi:[1,0]
	s_nop 0
	s_nop 0
	v_rcp_f32_e32 v65, v65
	s_nop 0
	s_nop 0
	v_rcp_f32_e32 v64, v64
	s_nop 0
	v_cvt_pk_bf16_f32 v66, v64, v65
	v_mul_f32_e32 v64, 0xbfb8aa3b, v76
	v_mul_f32_e32 v65, 0xbfb8aa3b, v77
	v_exp_f32_e32 v64, v64
	v_exp_f32_e32 v65, v65
	s_nop 0
	v_pk_add_f32 v[64:65], v[64:65], 1.0 op_sel_hi:[1,0]
	s_nop 0
	s_nop 0
	v_rcp_f32_e32 v65, v65
	s_nop 0
	s_nop 0
	v_rcp_f32_e32 v64, v64
	s_nop 0
	v_cvt_pk_bf16_f32 v64, v64, v65
	ds_write2st64_b32 v249, v66, v64 offset0:116 offset1:120
	v_mul_f32_e32 v64, 0xbfb8aa3b, v78
	v_mul_f32_e32 v65, 0xbfb8aa3b, v79
	v_exp_f32_e32 v64, v64
	v_exp_f32_e32 v65, v65
	s_nop 0
	v_pk_add_f32 v[64:65], v[64:65], 1.0 op_sel_hi:[1,0]
	s_nop 0
	s_nop 0
	v_rcp_f32_e32 v65, v65
	s_nop 0
	s_nop 0
	v_rcp_f32_e32 v64, v64
	s_nop 0
	v_cvt_pk_bf16_f32 v64, v64, v65
	ds_write_b32 v249, v64 offset:31744
	v_mov_b32_e32 v90, v232
	s_lshl_b64 s[0:1], s[0:1], 1
	s_add_u32 s36, s8, s0
	v_ashrrev_i32_e32 v80, 3, v90
	v_ashrrev_i32_e32 v81, 31, v80
	s_addc_u32 s37, s9, s1
	s_lshl_b32 s20, s20, 1
	v_lshlrev_b64 v[64:65], 11, v[80:81]
	v_lshlrev_b32_e32 v68, 4, v90
	s_add_u32 s38, s14, s20
	v_lshl_add_u64 v[66:67], s[36:37], 0, v[64:65]
	v_and_b32_e32 v224, 0x70, v68
	s_addc_u32 s39, s15, 0
	v_lshl_add_u64 v[82:83], v[66:67], 0, v[224:225]
	v_lshl_add_u64 v[64:65], s[38:39], 0, v[64:65]
	v_add_co_u32_e32 v72, vcc, s35, v82
	v_lshl_add_u64 v[84:85], v[64:65], 0, v[224:225]
	s_nop 0
	v_addc_co_u32_e32 v73, vcc, 0, v83, vcc
	v_add_co_u32_e32 v76, vcc, s35, v84
	s_waitcnt vmcnt(0)
;   u16* sA = (u16*)smem;
;   u16* sB = sA + 128 * LDT;
;   float* ss = (float*)(sB + 128 * LDT);
;   const int tid = TIDX(), lane = tid & 63, w = tid >> 6, wm = w >> 1, wn = w & 1;
;   const int srow = tid >> 3, scol = (tid & 7) * 8;
;   const u16* ap = A + (size_t)srow * lda + scol;
;   const u16* bp = B + (size_t)srow * ldb + scol;
;   bf16x8 ra[DEPTH][4], rb[DEPTH][4];
;   float ssq[4] = {0.f, 0.f, 0.f, 0.f};
;   const int nk = K >> 6;
; #pragma unroll
;   for (int d = 0; d < DEPTH; ++d)
; #pragma unroll
;     for (int i = 0; i < 4; ++i) {
;       ra[d][i] = *(const bf16x8*)(ap + d * 64 + (size_t)(32 * i) * lda);
;       rb[d][i] = *(const bf16x8*)(bp + d * 64 + (size_t)(32 * i) * ldb);
;     }
;   ap += DEPTH * 64;
;   bp += DEPTH * 64;
;   const int fro = (lane & 31) * LDT + (lane >> 5) * 8;
; DEV void zero_acc(f32x16 (&acc)[2][2]) {
; #pragma unroll
;   for (int a = 0; a < 2; ++a)
; #pragma unroll
;     for (int b = 0; b < 2; ++b)
; #pragma unroll
;       for (int r = 0; r < 16; ++r) acc[a][b][r] = 0.f;
; }
; DEV void phase_p5(const Params& p, int l, unsigned char* smem) {
;     ...
;     zero_acc(acc);
;     gemm_main<0>(acc, YA + (size_t)mt * 128 * 1024, 1024, WL + WO_BA + (size_t)nt * 128 * 1024, 1024, 1024, smem);
	v_mov_b32_e32 v64, v184
	v_mov_b32_e32 v65, v185
	v_mov_b32_e32 v66, v186
	v_mov_b32_e32 v67, v187
	v_mov_b32_e32 v68, v188
	v_mov_b32_e32 v69, v189
	v_mov_b32_e32 v70, v190
	v_mov_b32_e32 v71, v191
	v_addc_co_u32_e32 v77, vcc, 0, v85, vcc
	v_add_co_u32_e32 v86, vcc, s33, v82
	v_mov_b32_e32 v72, v192
	v_mov_b32_e32 v73, v193
	v_mov_b32_e32 v74, v194
	v_mov_b32_e32 v75, v195
	s_nop 0
	v_mov_b32_e32 v76, v196
	v_mov_b32_e32 v77, v197
	v_mov_b32_e32 v78, v198
	v_mov_b32_e32 v79, v199
	v_addc_co_u32_e32 v87, vcc, 0, v83, vcc
	v_add_co_u32_e32 v88, vcc, s33, v84
	s_waitcnt vmcnt(7)
	v_lshl_add_u64 v[160:161], v[82:83], 0, s[82:83]
	v_addc_co_u32_e32 v89, vcc, 0, v85, vcc
	v_mov_b32_e32 v96, v200
	v_mov_b32_e32 v97, v201
	v_mov_b32_e32 v98, v202
	v_mov_b32_e32 v99, v203
	v_mov_b32_e32 v100, v204
	v_mov_b32_e32 v101, v205
	v_mov_b32_e32 v102, v206
	v_mov_b32_e32 v103, v207
	v_add_co_u32_e32 v86, vcc, s40, v82
	v_lshl_add_u64 v[162:163], v[84:85], 0, s[82:83]
	s_nop 0
	v_addc_co_u32_e32 v87, vcc, 0, v83, vcc
	v_add_co_u32_e32 v88, vcc, s40, v84
	v_and_b32_e32 v82, 31, v90
	s_nop 0
	v_addc_co_u32_e32 v89, vcc, 0, v85, vcc
	v_mov_b32_e32 v104, v208
	v_mov_b32_e32 v105, v209
	v_mov_b32_e32 v106, v210
	v_mov_b32_e32 v107, v211
	v_mov_b32_e32 v108, v212
	v_mov_b32_e32 v109, v213
	v_mov_b32_e32 v110, v214
	v_mov_b32_e32 v111, v215
	v_lshrrev_b32_e32 v83, 2, v90
	v_lshrrev_b32_e32 v84, 1, v90
	v_and_b32_e32 v81, 64, v90
	v_mul_u32_u24_e32 v82, 0x48, v82
	v_and_b32_e32 v83, 8, v83
	v_and_b32_e32 v84, 0xfffffc0, v84
	v_add_lshl_u32 v82, v82, v83, 1
	s_waitcnt vmcnt(10)
	v_mad_u64_u32 v[164:165], s[36:37], v80, s49, v[224:225]
	v_mul_lo_u32 v83, v84, s49
	v_mul_u32_u24_e32 v81, 0x90, v81
	v_mov_b32_e32 v80, 0
	s_mov_b32 s21, 16
	v_add_u32_e32 v165, v82, v83
	v_add_u32_e32 v166, v82, v81
	v_mov_b32_e32 v81, v80
	v_mov_b32_e32 v82, v80
	v_mov_b32_e32 v83, v80
	v_mov_b32_e32 v84, v80
	v_mov_b32_e32 v85, v80
	v_mov_b32_e32 v86, v80
	v_mov_b32_e32 v87, v80
	v_mov_b32_e32 v88, v80
	v_mov_b32_e32 v89, v80
	v_mov_b32_e32 v90, v80
	v_mov_b32_e32 v91, v80
	v_mov_b32_e32 v92, v80
	v_mov_b32_e32 v93, v80
	v_mov_b32_e32 v94, v80
	v_mov_b32_e32 v95, v80
	v_mov_b32_e32 v112, v80
	v_mov_b32_e32 v113, v80
	v_mov_b32_e32 v114, v80
	v_mov_b32_e32 v115, v80
	v_mov_b32_e32 v116, v80
	v_mov_b32_e32 v117, v80
	v_mov_b32_e32 v118, v80
	v_mov_b32_e32 v119, v80
	v_mov_b32_e32 v120, v80
	v_mov_b32_e32 v121, v80
	v_mov_b32_e32 v122, v80
	v_mov_b32_e32 v123, v80
	v_mov_b32_e32 v124, v80
	v_mov_b32_e32 v125, v80
	v_mov_b32_e32 v126, v80
	v_mov_b32_e32 v127, v80
	v_mov_b32_e32 v128, v80
	v_mov_b32_e32 v129, v80
	v_mov_b32_e32 v130, v80
	v_mov_b32_e32 v131, v80
	v_mov_b32_e32 v132, v80
	v_mov_b32_e32 v133, v80
	v_mov_b32_e32 v134, v80
	v_mov_b32_e32 v135, v80
	v_mov_b32_e32 v136, v80
	v_mov_b32_e32 v137, v80
	v_mov_b32_e32 v138, v80
	v_mov_b32_e32 v139, v80
	v_mov_b32_e32 v140, v80
	v_mov_b32_e32 v141, v80
	v_mov_b32_e32 v142, v80
	v_mov_b32_e32 v143, v80
	v_mov_b32_e32 v144, v80
	v_mov_b32_e32 v145, v80
	v_mov_b32_e32 v146, v80
	v_mov_b32_e32 v147, v80
	v_mov_b32_e32 v148, v80
	v_mov_b32_e32 v149, v80
	v_mov_b32_e32 v150, v80
	v_mov_b32_e32 v151, v80
	v_mov_b32_e32 v152, v80
	v_mov_b32_e32 v153, v80
	v_mov_b32_e32 v154, v80
	v_mov_b32_e32 v155, v80
	v_mov_b32_e32 v156, v80
	v_mov_b32_e32 v157, v80
	v_mov_b32_e32 v158, v80
	v_mov_b32_e32 v159, v80
	s_branch .LBB0_1313
